# v083 + P2 sgu head loop software-pipelined: VT loads for head h+1 issued after head h's conversion into v130-v145 (prefetch), waits recounted, drain vmcnt(4) after the loop
# baseline (speedup 1.0000x reference)
.LBB0_395:
	s_or_b64 exec, exec, s[46:47]
	v_lshrrev_b32_e32 v3, 2, v18
	v_and_b32_e32 v3, 16, v3
	v_lshrrev_b32_e32 v4, 5, v18
	v_and_or_b32 v3, v4, 12, v3
	v_and_or_b32 v8, v0, s51, v3
	v_mul_lo_u32 v51, v8, s60
	v_add_u32_e32 v8, 0x200, v18
	v_ashrrev_i32_e32 v22, 4, v8
	v_and_or_b32 v8, v22, s51, v3
	v_mul_lo_u32 v52, v8, s60
	v_add_u32_e32 v8, 0x400, v18
	v_lshlrev_b32_e32 v6, 3, v19
	v_lshlrev_b32_e32 v50, 4, v19
	v_ashrrev_i32_e32 v19, 4, v8
	v_and_or_b32 v8, v19, s51, v3
	v_mul_lo_u32 v53, v8, s60
	v_add_u32_e32 v8, 0x600, v18
	v_ashrrev_i32_e32 v2, 7, v18
	v_ashrrev_i32_e32 v14, 4, v8
	s_and_b32 s33, s10, 1
	v_lshlrev_b32_e32 v5, 5, v2
	v_and_or_b32 v3, v14, s51, v3
	v_lshlrev_b32_e32 v2, 12, v2
	v_mul_lo_u32 v54, v3, s60
	v_lshlrev_b32_e32 v3, 7, v1
	v_lshl_add_u32 v2, s33, 16, v2
	s_lshl_b32 s8, s33, 9
	v_or3_b32 v56, v2, v3, v6
	v_add_u32_e32 v2, s8, v5
	s_lshr_b32 s46, s10, 1
	v_or_b32_e32 v2, v2, v1
	s_lshl_b32 s10, s46, 7
	v_ashrrev_i32_e32 v3, 31, v2
	v_lshl_add_u64 v[8:9], v[2:3], 2, s[36:37]
	v_add_u32_e32 v2, s10, v5
	v_and_b32_e32 v7, 64, v18
	v_or_b32_e32 v2, v2, v1
	v_lshl_add_u32 v48, v1, 5, 0
	v_lshlrev_b32_e32 v49, 4, v1
	v_and_b32_e32 v4, 0x4f, v18
	v_or3_b32 v1, v7, s8, v6
	v_ashrrev_i32_e32 v3, 31, v2
	v_mul_u32_u24_e32 v55, 0x110, v4
	v_or_b32_e32 v4, 16, v2
	v_lshl_or_b32 v6, v1, 1, v115
	v_mov_b32_e32 v7, v61
	v_lshlrev_b64 v[2:3], 12, v[2:3]
	v_lshl_add_u64 v[12:13], v[2:3], 0, v[6:7]
	v_add_u32_e32 v2, s8, v14
	v_ashrrev_i32_e32 v3, 31, v2
	v_lshl_add_u64 v[14:15], v[2:3], 2, s[24:25]
	v_lshlrev_b64 v[2:3], 15, v[2:3]
	v_or_b32_e32 v2, s64, v2
	v_lshl_add_u64 v[2:3], v[2:3], 0, v[60:61]
	v_lshl_add_u64 v[16:17], v[2:3], 0, s[42:43]
	v_add_u32_e32 v2, s8, v19
	v_ashrrev_i32_e32 v3, 31, v2
	v_lshl_add_u64 v[18:19], v[2:3], 2, s[24:25]
	v_lshlrev_b64 v[2:3], 15, v[2:3]
	v_or_b32_e32 v2, s64, v2
	v_lshl_add_u64 v[2:3], v[2:3], 0, v[60:61]
	v_lshl_add_u64 v[20:21], v[2:3], 0, s[42:43]
	v_add_u32_e32 v2, s8, v22
	v_add_u32_e32 v0, s8, v0
	v_ashrrev_i32_e32 v3, 31, v2
	v_ashrrev_i32_e32 v1, 31, v0
	v_lshl_add_u64 v[22:23], v[2:3], 2, s[24:25]
	v_lshlrev_b64 v[2:3], 15, v[2:3]
	v_lshl_add_u64 v[26:27], v[0:1], 2, s[24:25]
	v_lshlrev_b64 v[0:1], 15, v[0:1]
	v_ashrrev_i32_e32 v5, 31, v4
	v_or_b32_e32 v2, s64, v2
	v_or_b32_e32 v0, s64, v0
	v_lshlrev_b64 v[4:5], 12, v[4:5]
	v_lshl_add_u64 v[2:3], v[2:3], 0, v[60:61]
	v_lshl_add_u64 v[0:1], v[0:1], 0, v[60:61]
	s_lshl_b32 s47, s33, 2
	v_lshl_add_u64 v[10:11], v[4:5], 0, v[6:7]
	v_lshl_add_u64 v[24:25], v[2:3], 0, s[42:43]
	v_lshl_add_u64 v[28:29], v[0:1], 0, s[42:43]
	v_lshl_add_u64 v[154:155], s[56:57], 0, v[28:29]
	global_load_dwordx4 v[130:133], v[154:155], off
	v_lshl_add_u64 v[156:157], s[56:57], 0, v[24:25]
	global_load_dwordx4 v[134:137], v[156:157], off
	v_lshl_add_u64 v[154:155], s[56:57], 0, v[20:21]
	global_load_dwordx4 v[138:141], v[154:155], off
	v_lshl_add_u64 v[156:157], s[56:57], 0, v[16:17]
	global_load_dwordx4 v[142:145], v[156:157], off
	s_mov_b32 s64, 0
	s_mov_b64 s[8:9], 0
	s_waitcnt lgkmcnt(0)
	s_barrier
.LBB0_396:
	v_lshl_add_u64 v[30:31], s[56:57], 0, v[28:29]
	v_lshl_add_u64 v[32:33], v[26:27], 0, s[8:9]
	v_lshl_add_u64 v[36:37], v[22:23], 0, s[8:9]
	ds_read_b128 v[4:7], v48 offset:4096
	ds_read_b128 v[0:3], v48 offset:4112
	v_lshl_add_u64 v[38:39], s[56:57], 0, v[24:25]
	v_lshl_add_u64 v[46:47], s[56:57], 0, v[20:21]
	v_lshl_add_u64 v[58:59], s[56:57], 0, v[16:17]
	global_load_dword v60, v[32:33], off
	s_nop 0
	s_nop 0
	s_nop 0
	global_load_dword v36, v[36:37], off
	v_lshl_add_u64 v[44:45], v[18:19], 0, s[8:9]
	v_lshl_add_u64 v[74:75], v[14:15], 0, s[8:9]
	global_load_dword v38, v[44:45], off
	s_nop 0
	global_load_dword v44, v[74:75], off
	s_bitcmp1_b32 s47, 0
	s_cselect_b32 s65, 0x8800, 0
	s_add_i32 s65, s65, 0
	v_add_u32_e32 v37, s65, v49
	v_add_u32_e32 v39, v37, v51
	v_add_u32_e32 v42, s64, v56
	v_ashrrev_i32_e32 v43, 31, v42
	v_lshl_add_u64 v[74:75], v[42:43], 1, s[38:39]
	v_add_u32_e32 v43, v37, v52
	v_add_u32_e32 v45, v37, v53
	v_add_u32_e32 v37, v37, v54
	v_add_u32_e32 v46, 0x800, v42
	v_ashrrev_i32_e32 v47, 31, v46
	v_lshl_add_u64 v[46:47], v[46:47], 1, s[38:39]
	v_add3_u32 v57, s65, v50, v55
	v_add_u32_e32 v58, 32, v42
	v_add_u32_e32 v94, 0x820, v42
	v_ashrrev_i32_e32 v59, 31, v58
	v_add_u32_e32 v100, 64, v42
	v_add_u32_e32 v102, 0x840, v42
	v_add_u32_e32 v104, 0x60, v42
	v_add_u32_e32 v106, 0x860, v42
	v_ashrrev_i32_e32 v95, 31, v94
	v_ashrrev_i32_e32 v101, 31, v100
	v_ashrrev_i32_e32 v103, 31, v102
	v_lshl_add_u64 v[98:99], s[56:57], 0, v[12:13]
	v_add_co_u32_e32 v110, vcc, s61, v98
	v_ashrrev_i32_e32 v105, 31, v104
	s_nop 0
	v_addc_co_u32_e32 v111, vcc, 0, v99, vcc
	v_lshl_add_u64 v[120:121], v[104:105], 1, s[38:39]
	v_ashrrev_i32_e32 v107, 31, v106
	v_lshl_add_u64 v[40:41], v[8:9], 0, s[8:9]
	v_lshl_add_u64 v[128:129], v[106:107], 1, s[38:39]
	v_lshl_add_u64 v[34:35], s[56:57], 0, v[10:11]
	v_add_co_u32_e32 v236, vcc, s61, v34
	global_load_dwordx4 v[176:179], v[74:75], off
	global_load_dwordx4 v[180:183], v[46:47], off
	v_addc_co_u32_e32 v237, vcc, 0, v35, vcc
	v_lshl_add_u64 v[228:229], v[58:59], 1, s[38:39]
	v_lshl_add_u64 v[230:231], v[94:95], 1, s[38:39]
	v_lshl_add_u64 v[232:233], v[100:101], 1, s[38:39]
	v_lshl_add_u64 v[234:235], v[102:103], 1, s[38:39]
	global_load_dwordx4 v[184:187], v[228:229], off
	global_load_dwordx4 v[188:191], v[230:231], off
	global_load_dwordx4 v[192:195], v[232:233], off
	global_load_dwordx4 v[196:199], v[234:235], off
	global_load_dwordx4 v[200:203], v[120:121], off
	global_load_dwordx4 v[204:207], v[128:129], off
	global_load_dwordx4 v[208:211], v[110:111], off
	global_load_dwordx4 v[212:215], v[110:111], off offset:64
	global_load_dword v224, v[40:41], off offset:-64
	global_load_dwordx4 v[216:219], v[236:237], off
	global_load_dwordx4 v[220:223], v[236:237], off offset:64
	global_load_dword v226, v[40:41], off
	s_add_i32 s47, s47, 1
	s_addk_i32 s64, 0x4000
	s_add_u32 s8, s8, 0x200
	s_addc_u32 s9, s9, 0
	v_lshl_add_u64 v[10:11], v[10:11], 0, s[44:45]
	v_lshl_add_u64 v[12:13], v[12:13], 0, s[44:45]
	v_lshl_add_u64 v[16:17], v[16:17], 0, s[40:41]
	v_lshl_add_u64 v[20:21], v[20:21], 0, s[40:41]
	v_lshl_add_u64 v[24:25], v[24:25], 0, s[40:41]
	v_lshl_add_u64 v[28:29], v[28:29], 0, s[40:41]
	s_cmp_lg_u32 s64, 0x10000
	s_waitcnt vmcnt(17) lgkmcnt(1)
	v_pk_mul_f32 v[6:7], v[6:7], v[60:61] op_sel_hi:[1,0]
	v_pk_mul_f32 v[4:5], v[4:5], v[60:61] op_sel_hi:[1,0]
	s_waitcnt lgkmcnt(0)
	v_pk_mul_f32 v[2:3], v[2:3], v[60:61] op_sel_hi:[1,0]
	v_pk_mul_f32 v[0:1], v[0:1], v[60:61] op_sel_hi:[1,0]
	s_waitcnt vmcnt(17)
	v_lshlrev_b32_e32 v76, 16, v130
	v_and_b32_e32 v77, 0xffff0000, v130
	v_lshlrev_b32_e32 v30, 16, v131
	v_and_b32_e32 v31, 0xffff0000, v131
	v_lshlrev_b32_e32 v78, 16, v132
	v_and_b32_e32 v79, 0xffff0000, v132
	v_lshlrev_b32_e32 v32, 16, v133
	v_and_b32_e32 v33, 0xffff0000, v133
	v_pk_mul_f32 v[4:5], v[4:5], v[76:77]
	v_pk_mul_f32 v[6:7], v[6:7], v[30:31]
	v_pk_mul_f32 v[30:31], v[0:1], v[78:79]
	v_pk_mul_f32 v[32:33], v[2:3], v[32:33]
	v_cvt_pk_bf16_f32 v0, v4, v5
	v_cvt_pk_bf16_f32 v1, v6, v7
	v_cvt_pk_bf16_f32 v2, v30, v31
	v_cvt_pk_bf16_f32 v3, v32, v33
	ds_write_b128 v39, v[0:3] offset:8192
	ds_read_b128 v[0:3], v48 offset:4096
	ds_read_b128 v[4:7], v48 offset:4112
	s_waitcnt vmcnt(17)
	v_lshlrev_b32_e32 v80, 16, v134
	v_and_b32_e32 v81, 0xffff0000, v134
	v_lshlrev_b32_e32 v62, 16, v135
	v_and_b32_e32 v63, 0xffff0000, v135
	v_lshlrev_b32_e32 v82, 16, v136
	v_and_b32_e32 v83, 0xffff0000, v136
	v_lshlrev_b32_e32 v64, 16, v137
	v_and_b32_e32 v65, 0xffff0000, v137
	s_waitcnt vmcnt(16) lgkmcnt(1)
	v_pk_mul_f32 v[2:3], v[2:3], v[36:37] op_sel_hi:[1,0]
	v_pk_mul_f32 v[0:1], v[0:1], v[36:37] op_sel_hi:[1,0]
	s_waitcnt lgkmcnt(0)
	v_pk_mul_f32 v[6:7], v[6:7], v[36:37] op_sel_hi:[1,0]
	v_pk_mul_f32 v[4:5], v[4:5], v[36:37] op_sel_hi:[1,0]
	v_pk_mul_f32 v[0:1], v[0:1], v[80:81]
	v_pk_mul_f32 v[2:3], v[2:3], v[62:63]
	v_pk_mul_f32 v[4:5], v[4:5], v[82:83]
	v_pk_mul_f32 v[6:7], v[6:7], v[64:65]
	v_cvt_pk_bf16_f32 v0, v0, v1
	v_cvt_pk_bf16_f32 v1, v2, v3
	v_cvt_pk_bf16_f32 v2, v4, v5
	v_cvt_pk_bf16_f32 v3, v6, v7
	ds_write_b128 v43, v[0:3] offset:8192
	ds_read_b128 v[0:3], v48 offset:4096
	ds_read_b128 v[4:7], v48 offset:4112
	v_lshlrev_b32_e32 v84, 16, v138
	v_and_b32_e32 v85, 0xffff0000, v138
	v_lshlrev_b32_e32 v66, 16, v139
	v_and_b32_e32 v67, 0xffff0000, v139
	v_lshlrev_b32_e32 v86, 16, v140
	v_and_b32_e32 v87, 0xffff0000, v140
	v_lshlrev_b32_e32 v68, 16, v141
	v_and_b32_e32 v69, 0xffff0000, v141
	s_waitcnt vmcnt(15) lgkmcnt(1)
	v_pk_mul_f32 v[2:3], v[2:3], v[38:39] op_sel_hi:[1,0]
	v_pk_mul_f32 v[0:1], v[0:1], v[38:39] op_sel_hi:[1,0]
	s_waitcnt lgkmcnt(0)
	v_pk_mul_f32 v[6:7], v[6:7], v[38:39] op_sel_hi:[1,0]
	v_pk_mul_f32 v[4:5], v[4:5], v[38:39] op_sel_hi:[1,0]
	v_pk_mul_f32 v[0:1], v[0:1], v[84:85]
	v_pk_mul_f32 v[2:3], v[2:3], v[66:67]
	v_pk_mul_f32 v[4:5], v[4:5], v[86:87]
	v_pk_mul_f32 v[6:7], v[6:7], v[68:69]
	v_cvt_pk_bf16_f32 v0, v0, v1
	v_cvt_pk_bf16_f32 v1, v2, v3
	v_cvt_pk_bf16_f32 v2, v4, v5
	v_cvt_pk_bf16_f32 v3, v6, v7
	ds_write_b128 v45, v[0:3] offset:8192
	ds_read_b128 v[0:3], v48 offset:4096
	ds_read_b128 v[4:7], v48 offset:4112
	v_lshlrev_b32_e32 v88, 16, v142
	v_and_b32_e32 v89, 0xffff0000, v142
	v_lshlrev_b32_e32 v70, 16, v143
	v_and_b32_e32 v71, 0xffff0000, v143
	v_lshlrev_b32_e32 v90, 16, v144
	v_and_b32_e32 v91, 0xffff0000, v144
	v_lshlrev_b32_e32 v72, 16, v145
	v_and_b32_e32 v73, 0xffff0000, v145
	v_lshl_add_u64 v[154:155], s[56:57], 0, v[28:29]
	global_load_dwordx4 v[130:133], v[154:155], off
	v_lshl_add_u64 v[156:157], s[56:57], 0, v[24:25]
	global_load_dwordx4 v[134:137], v[156:157], off
	v_lshl_add_u64 v[154:155], s[56:57], 0, v[20:21]
	global_load_dwordx4 v[138:141], v[154:155], off
	v_lshl_add_u64 v[156:157], s[56:57], 0, v[16:17]
	global_load_dwordx4 v[142:145], v[156:157], off
	s_waitcnt vmcnt(14) lgkmcnt(1)
	v_pk_mul_f32 v[2:3], v[2:3], v[44:45] op_sel_hi:[1,0]
	v_pk_mul_f32 v[0:1], v[0:1], v[44:45] op_sel_hi:[1,0]
	s_waitcnt lgkmcnt(0)
	v_pk_mul_f32 v[6:7], v[6:7], v[44:45] op_sel_hi:[1,0]
	v_pk_mul_f32 v[4:5], v[4:5], v[44:45] op_sel_hi:[1,0]
	v_pk_mul_f32 v[0:1], v[0:1], v[88:89]
	v_pk_mul_f32 v[2:3], v[2:3], v[70:71]
	v_pk_mul_f32 v[4:5], v[4:5], v[90:91]
	v_pk_mul_f32 v[6:7], v[6:7], v[72:73]
	v_cvt_pk_bf16_f32 v0, v0, v1
	v_cvt_pk_bf16_f32 v1, v2, v3
	v_cvt_pk_bf16_f32 v2, v4, v5
	v_cvt_pk_bf16_f32 v3, v6, v7
	ds_write_b128 v37, v[0:3] offset:8192
	s_waitcnt lgkmcnt(0)
	s_barrier
	ds_read_b128 v[30:33], v57 offset:8192
	ds_read_b128 v[36:39], v57 offset:8256
	ds_read_b128 v[62:65], v57 offset:12544
	ds_read_b128 v[66:69], v57 offset:12608
	ds_read_b128 v[74:77], v57 offset:16896
	ds_read_b128 v[78:81], v57 offset:16960
	ds_read_b128 v[86:89], v57 offset:21248
	ds_read_b128 v[90:93], v57 offset:21312
	v_lshl_add_u64 v[42:43], v[58:59], 1, s[38:39]
	v_lshl_add_u64 v[58:59], v[94:95], 1, s[38:39]
	s_waitcnt vmcnt(17) lgkmcnt(7)
	v_mfma_f32_16x16x32_bf16 v[44:47], v[30:33], v[176:179], 0
	s_waitcnt lgkmcnt(5)
	v_mfma_f32_16x16x32_bf16 v[70:73], v[62:65], v[176:179], 0
	s_waitcnt lgkmcnt(3)
	v_mfma_f32_16x16x32_bf16 v[82:85], v[74:77], v[176:179], 0
	s_waitcnt lgkmcnt(1)
	v_mfma_f32_16x16x32_bf16 v[0:3], v[86:89], v[176:179], 0
	s_waitcnt vmcnt(16)
	v_mfma_f32_16x16x32_bf16 v[30:33], v[30:33], v[180:183], 0
	v_mfma_f32_16x16x32_bf16 v[62:65], v[62:65], v[180:183], 0
	v_mfma_f32_16x16x32_bf16 v[74:77], v[74:77], v[180:183], 0
	v_mfma_f32_16x16x32_bf16 v[4:7], v[86:89], v[180:183], 0
	s_waitcnt vmcnt(15)
	v_mfma_f32_16x16x32_bf16 v[42:45], v[36:39], v[184:187], v[44:47]
	v_mfma_f32_16x16x32_bf16 v[70:73], v[66:69], v[184:187], v[70:73]
	s_nop 1
	v_add_co_u32_e32 v46, vcc, s62, v98
	v_mfma_f32_16x16x32_bf16 v[82:85], v[78:81], v[184:187], v[82:85]
	s_nop 0
	v_addc_co_u32_e32 v47, vcc, 0, v99, vcc
	v_add_co_u32_e32 v58, vcc, s61, v34
	s_waitcnt lgkmcnt(0)
	v_mfma_f32_16x16x32_bf16 v[0:3], v[90:93], v[184:187], v[0:3]
	v_lshl_add_u64 v[94:95], v[100:101], 1, s[38:39]
	v_lshl_add_u64 v[96:97], v[102:103], 1, s[38:39]
	v_addc_co_u32_e32 v59, vcc, 0, v35, vcc
	s_waitcnt vmcnt(14)
	v_mfma_f32_16x16x32_bf16 v[30:33], v[36:39], v[188:191], v[30:33]
	v_add_co_u32_e32 v34, vcc, s62, v34
	v_mfma_f32_16x16x32_bf16 v[36:39], v[66:69], v[188:191], v[62:65]
	s_nop 0
	v_addc_co_u32_e32 v35, vcc, 0, v35, vcc
	s_nop 0
	v_mfma_f32_16x16x32_bf16 v[66:69], v[78:81], v[188:191], v[74:77]
	s_nop 2
	v_mfma_f32_16x16x32_bf16 v[4:7], v[90:93], v[188:191], v[4:7]
	ds_read_b128 v[78:81], v57 offset:8320
	ds_read_b128 v[86:89], v57 offset:8384
	ds_read_b128 v[90:93], v57 offset:12672
	ds_read_b128 v[94:97], v57 offset:12736
	ds_read_b128 v[98:101], v57 offset:17024
	ds_read_b128 v[102:105], v57 offset:17088
	ds_read_b128 v[116:119], v57 offset:21376
	ds_read_b128 v[124:127], v57 offset:21440
	s_waitcnt vmcnt(13) lgkmcnt(7)
	v_mfma_f32_16x16x32_bf16 v[42:45], v[78:81], v[192:195], v[42:45]
	s_waitcnt lgkmcnt(5)
	v_mfma_f32_16x16x32_bf16 v[70:73], v[90:93], v[192:195], v[70:73]
	s_waitcnt lgkmcnt(3)
	v_mfma_f32_16x16x32_bf16 v[82:85], v[98:101], v[192:195], v[82:85]
	s_waitcnt lgkmcnt(1)
	v_mfma_f32_16x16x32_bf16 v[0:3], v[116:119], v[192:195], v[0:3]
	s_waitcnt vmcnt(9)
	v_lshlrev_b32_e32 v110, 16, v208
	v_mfma_f32_16x16x32_bf16 v[30:33], v[78:81], v[196:199], v[30:33]
	v_and_b32_e32 v111, 0xffff0000, v208
	s_waitcnt vmcnt(8)
	v_lshlrev_b32_e32 v106, 16, v214
	v_mfma_f32_16x16x32_bf16 v[42:45], v[86:89], v[200:203], v[42:45]
	v_mfma_f32_16x16x32_bf16 v[70:73], v[94:97], v[200:203], v[70:73]
	v_mfma_f32_16x16x32_bf16 v[82:85], v[102:105], v[200:203], v[82:85]
	s_waitcnt vmcnt(7)
	s_nop 4
	v_pk_add_f32 v[44:45], v[44:45], v[224:225] op_sel_hi:[1,0]
	s_waitcnt lgkmcnt(0)
	v_mfma_f32_16x16x32_bf16 v[0:3], v[124:127], v[200:203], v[0:3]
	v_add_f32_e64 v42, v42, v224
	v_add_f32_e64 v43, v43, v224
	v_pk_add_f32 v[72:73], v[72:73], v[224:225] op_sel_hi:[1,0]
	v_pk_add_f32 v[70:71], v[70:71], v[224:225] op_sel_hi:[1,0]
	v_mfma_f32_16x16x32_bf16 v[36:39], v[90:93], v[196:199], v[36:39]
	v_lshlrev_b32_e32 v90, 16, v209
	v_and_b32_e32 v91, 0xffff0000, v209
	v_lshlrev_b32_e32 v92, 16, v210
	v_mfma_f32_16x16x32_bf16 v[66:69], v[98:101], v[196:199], v[66:69]
	v_and_b32_e32 v93, 0xffff0000, v210
	v_lshlrev_b32_e32 v98, 16, v211
	v_and_b32_e32 v99, 0xffff0000, v211
	v_lshlrev_b32_e32 v100, 16, v212
	v_and_b32_e32 v101, 0xffff0000, v212
	v_lshlrev_b32_e32 v62, 16, v213
	v_and_b32_e32 v63, 0xffff0000, v213
	v_and_b32_e32 v107, 0xffff0000, v214
	v_lshlrev_b32_e32 v64, 16, v215
	v_and_b32_e32 v65, 0xffff0000, v215
	v_pk_add_f32 v[84:85], v[84:85], v[224:225] op_sel_hi:[1,0]
	v_pk_add_f32 v[82:83], v[82:83], v[224:225] op_sel_hi:[1,0]
	v_pk_add_f32 v[2:3], v[2:3], v[224:225] op_sel_hi:[1,0]
	v_pk_add_f32 v[0:1], v[0:1], v[224:225] op_sel_hi:[1,0]
	v_pk_mul_f32 v[42:43], v[42:43], v[110:111]
	v_pk_mul_f32 v[44:45], v[44:45], v[90:91]
	v_pk_mul_f32 v[70:71], v[70:71], v[92:93]
	v_pk_mul_f32 v[72:73], v[72:73], v[98:99]
	v_pk_mul_f32 v[82:83], v[82:83], v[100:101]
	v_pk_mul_f32 v[62:63], v[84:85], v[62:63]
	v_pk_mul_f32 v[84:85], v[0:1], v[106:107]
	v_pk_mul_f32 v[64:65], v[2:3], v[64:65]
	v_cvt_pk_bf16_f32 v0, v42, v43
	v_cvt_pk_bf16_f32 v1, v44, v45
	v_cvt_pk_bf16_f32 v2, v70, v71
	v_cvt_pk_bf16_f32 v3, v72, v73
	v_cvt_pk_bf16_f32 v42, v82, v83
	v_cvt_pk_bf16_f32 v43, v62, v63
	v_cvt_pk_bf16_f32 v44, v84, v85
	v_cvt_pk_bf16_f32 v45, v64, v65
	global_store_dwordx4 v[46:47], v[0:3], off
	global_store_dwordx4 v[46:47], v[42:45], off offset:64
	s_nop 0
	v_mfma_f32_16x16x32_bf16 v[4:7], v[116:119], v[196:199], v[4:7]
	s_waitcnt vmcnt(6)
	v_lshlrev_b32_e32 v58, 16, v216
	v_mfma_f32_16x16x32_bf16 v[30:33], v[86:89], v[204:207], v[30:33]
	v_and_b32_e32 v59, 0xffff0000, v216
	v_lshlrev_b32_e32 v0, 16, v217
	v_and_b32_e32 v1, 0xffff0000, v217
	v_mfma_f32_16x16x32_bf16 v[36:39], v[94:97], v[204:207], v[36:39]
	v_lshlrev_b32_e32 v62, 16, v218
	s_nop 2
	v_pk_add_f32 v[32:33], v[32:33], v[226:227] op_sel_hi:[1,0]
	v_pk_add_f32 v[30:31], v[30:31], v[226:227] op_sel_hi:[1,0]
	v_mfma_f32_16x16x32_bf16 v[44:47], v[102:105], v[204:207], v[66:69]
	v_and_b32_e32 v63, 0xffff0000, v218
	v_pk_add_f32 v[38:39], v[38:39], v[226:227] op_sel_hi:[1,0]
	v_pk_add_f32 v[36:37], v[36:37], v[226:227] op_sel_hi:[1,0]
	v_mfma_f32_16x16x32_bf16 v[4:7], v[124:127], v[204:207], v[4:7]
	v_lshlrev_b32_e32 v2, 16, v219
	v_and_b32_e32 v3, 0xffff0000, v219
	s_nop 1
	v_pk_add_f32 v[46:47], v[46:47], v[226:227] op_sel_hi:[1,0]
	v_pk_add_f32 v[44:45], v[44:45], v[226:227] op_sel_hi:[1,0]
	s_waitcnt vmcnt(6)
	v_lshlrev_b32_e32 v64, 16, v220
	v_pk_add_f32 v[6:7], v[6:7], v[226:227] op_sel_hi:[1,0]
	v_pk_add_f32 v[4:5], v[4:5], v[226:227] op_sel_hi:[1,0]
	v_and_b32_e32 v65, 0xffff0000, v220
	v_lshlrev_b32_e32 v40, 16, v221
	v_and_b32_e32 v41, 0xffff0000, v221
	v_lshlrev_b32_e32 v66, 16, v222
	v_and_b32_e32 v67, 0xffff0000, v222
	v_lshlrev_b32_e32 v42, 16, v223
	v_and_b32_e32 v43, 0xffff0000, v223
	v_pk_mul_f32 v[30:31], v[30:31], v[58:59]
	v_pk_mul_f32 v[32:33], v[32:33], v[0:1]
	v_pk_mul_f32 v[36:37], v[36:37], v[62:63]
	v_pk_mul_f32 v[38:39], v[38:39], v[2:3]
	v_pk_mul_f32 v[44:45], v[44:45], v[64:65]
	v_pk_mul_f32 v[40:41], v[46:47], v[40:41]
	v_pk_mul_f32 v[46:47], v[4:5], v[66:67]
	v_pk_mul_f32 v[42:43], v[6:7], v[42:43]
	v_cvt_pk_bf16_f32 v0, v30, v31
	v_cvt_pk_bf16_f32 v1, v32, v33
	v_cvt_pk_bf16_f32 v2, v36, v37
	v_cvt_pk_bf16_f32 v3, v38, v39
	v_cvt_pk_bf16_f32 v4, v44, v45
	v_cvt_pk_bf16_f32 v5, v40, v41
	v_cvt_pk_bf16_f32 v6, v46, v47
	v_cvt_pk_bf16_f32 v7, v42, v43
	global_store_dwordx4 v[34:35], v[0:3], off
	global_store_dwordx4 v[34:35], v[4:7], off offset:64
	s_cbranch_scc1 .LBB0_396
	s_waitcnt vmcnt(4)
	v_mov_b32_e32 v0, v174
	s_barrier
	s_and_b32 s10, s10, 0xf80
	s_lshl_b32 s46, s46, 19
	v_ashrrev_i32_e32 v1, 2, v0
	s_add_u32 s8, s12, s46
	v_lshlrev_b32_e32 v0, 4, v0
	s_addc_u32 s9, s13, 0
	v_and_b32_e32 v60, 0x1f0, v0
	v_and_b32_e32 v66, -8, v1
	v_lshl_add_u64 v[64:65], s[8:9], 0, v[60:61]
	s_add_u32 s8, s66, s46
	s_addc_u32 s9, s67, 0
	v_or_b32_e32 v80, 1, v66
	v_or_b32_e32 v78, 2, v66
	v_or_b32_e32 v76, 3, v66
	v_or_b32_e32 v74, 4, v66
	v_or_b32_e32 v72, 5, v66
	v_or_b32_e32 v70, 6, v66
	v_or_b32_e32 v68, 7, v1
	v_lshl_add_u64 v[62:63], s[8:9], 0, v[60:61]
	s_mov_b64 s[8:9], -1
	s_cmp_lg_u32 s33, 0
	v_add_u32_e32 v124, -3, v66
	v_add_u32_e32 v123, -2, v66
	v_add_u32_e32 v125, -1, v66
	v_add_u32_e32 v122, s10, v66
	v_ashrrev_i32_e32 v67, 31, v66
	v_add_u32_e32 v121, s10, v80
	v_ashrrev_i32_e32 v81, 31, v80
	v_add_u32_e32 v120, s10, v78
	v_ashrrev_i32_e32 v79, 31, v78
	v_add_u32_e32 v119, s10, v76
	v_ashrrev_i32_e32 v77, 31, v76
	v_add_u32_e32 v118, s10, v74
	v_ashrrev_i32_e32 v75, 31, v74
	v_add_u32_e32 v117, s10, v72
	v_ashrrev_i32_e32 v73, 31, v72
	v_add_u32_e32 v116, s10, v70
	v_ashrrev_i32_e32 v71, 31, v70
	v_add_u32_e32 v60, s10, v68
	s_cbranch_scc0 .LBB0_399
	s_sub_i32 s8, 0, s10
	v_max_i32_e32 v0, s8, v124
	v_ashrrev_i32_e32 v1, 31, v0
	v_lshlrev_b64 v[0:1], 12, v[0:1]
	v_lshl_add_u64 v[22:23], v[64:65], 0, v[0:1]
	v_max_i32_e32 v0, s8, v123
	v_ashrrev_i32_e32 v1, 31, v0
	v_lshlrev_b64 v[0:1], 12, v[0:1]
	v_lshl_add_u64 v[28:29], v[64:65], 0, v[0:1]
	v_max_i32_e32 v0, s8, v125
	v_ashrrev_i32_e32 v1, 31, v0
	global_load_dwordx4 v[4:7], v[22:23], off offset:512
	v_lshlrev_b64 v[0:1], 12, v[0:1]
	global_load_dwordx4 v[8:11], v[28:29], off offset:512
	v_lshl_add_u64 v[30:31], v[64:65], 0, v[0:1]
	v_max_i32_e32 v0, s8, v66
	global_load_dwordx4 v[12:15], v[30:31], off offset:512
	v_ashrrev_i32_e32 v1, 31, v0
	v_lshlrev_b64 v[0:1], 12, v[0:1]
	v_lshl_add_u64 v[20:21], v[64:65], 0, v[0:1]
	global_load_dwordx4 v[0:3], v[20:21], off offset:512
	v_min_i32_e32 v17, 3, v122
	v_max_i32_e32 v16, s8, v80
	v_max_i32_e32 v18, s8, v78
	v_max_i32_e32 v24, s8, v76
	v_max_i32_e32 v26, s8, v74
	v_max_i32_e32 v32, s8, v72
	v_add_u32_e32 v35, 1, v17
	v_ashrrev_i32_e32 v17, 31, v16
	v_ashrrev_i32_e32 v19, 31, v18
	v_ashrrev_i32_e32 v25, 31, v24
	v_ashrrev_i32_e32 v27, 31, v26
	v_ashrrev_i32_e32 v33, 31, v32
	v_lshlrev_b64 v[16:17], 12, v[16:17]
	v_lshlrev_b64 v[18:19], 12, v[18:19]
	v_lshlrev_b64 v[24:25], 12, v[24:25]
	v_lshlrev_b64 v[26:27], 12, v[26:27]
	v_lshlrev_b64 v[40:41], 12, v[32:33]
	v_lshl_add_u64 v[32:33], v[64:65], 0, v[16:17]
	v_lshl_add_u64 v[84:85], v[64:65], 0, v[18:19]
	v_lshl_add_u64 v[58:59], v[64:65], 0, v[24:25]
	v_lshl_add_u64 v[56:57], v[64:65], 0, v[26:27]
	global_load_dwordx4 v[24:27], v[32:33], off offset:512
	global_load_dwordx4 v[16:19], v[84:85], off offset:512
	global_load_dwordx4 v[48:51], v[22:23], off offset:1024
	global_load_dwordx4 v[44:47], v[28:29], off offset:1024
	v_cvt_f32_i32_e32 v35, v35
	v_max_i32_e32 v36, s8, v70
	v_max_i32_e32 v38, s8, v68
	v_ashrrev_i32_e32 v37, 31, v36
	v_div_scale_f32 v22, s[46:47], v35, v35, 1.0
	v_rcp_f32_e32 v23, v22
	v_ashrrev_i32_e32 v39, 31, v38
	v_div_scale_f32 v28, vcc, 1.0, v35, 1.0
	v_fma_f32 v29, -v22, v23, 1.0
	v_fmac_f32_e32 v23, v29, v23
	v_lshlrev_b64 v[36:37], 12, v[36:37]
	v_lshlrev_b64 v[38:39], 12, v[38:39]
	v_mul_f32_e32 v29, v28, v23
	v_lshl_add_u64 v[54:55], v[64:65], 0, v[40:41]
	v_lshl_add_u64 v[52:53], v[64:65], 0, v[36:37]
	v_lshl_add_u64 v[82:83], v[64:65], 0, v[38:39]
	global_load_dwordx4 v[40:43], v[30:31], off offset:1024
	global_load_dwordx4 v[36:39], v[20:21], off offset:1024
	v_fma_f32 v30, -v22, v29, v28
	v_fmac_f32_e32 v29, v30, v23
	v_add_u32_e32 v34, s10, v124
	v_fma_f32 v22, -v22, v29, v28
	v_div_fmas_f32 v22, v22, v23, v29
	v_cmp_lt_i32_e32 vcc, -1, v34
	s_waitcnt vmcnt(6)
	v_lshlrev_b32_e32 v134, 16, v1
	v_cndmask_b32_e32 v23, 0, v7, vcc
	v_cndmask_b32_e32 v28, 0, v6, vcc
	v_cndmask_b32_e32 v5, 0, v5, vcc
	v_cndmask_b32_e32 v6, 0, v4, vcc
	v_cmp_lt_i32_e32 vcc, -2, v34
	v_lshlrev_b32_e32 v128, 16, v5
	v_and_b32_e32 v129, 0xffff0000, v5
	v_cndmask_b32_e32 v29, 0, v11, vcc
	v_cndmask_b32_e32 v10, 0, v10, vcc
	v_cndmask_b32_e32 v11, 0, v9, vcc
	v_cndmask_b32_e32 v8, 0, v8, vcc
	v_cmp_lt_i32_e32 vcc, -3, v34
	v_lshlrev_b32_e32 v106, 16, v8
	v_and_b32_e32 v107, 0xffff0000, v8
	v_cndmask_b32_e32 v9, 0, v12, vcc
	v_cndmask_b32_e32 v13, 0, v13, vcc
	v_lshlrev_b32_e32 v108, 16, v9
	v_and_b32_e32 v109, 0xffff0000, v9
	v_pk_add_f32 v[8:9], v[128:129], 0 op_sel_hi:[1,0]
	v_lshlrev_b32_e32 v130, 16, v11
	v_and_b32_e32 v131, 0xffff0000, v11
	v_pk_add_f32 v[8:9], v[8:9], v[130:131]
	v_lshlrev_b32_e32 v132, 16, v13
	v_and_b32_e32 v133, 0xffff0000, v13
	v_lshlrev_b32_e32 v86, 16, v6
	v_and_b32_e32 v87, 0xffff0000, v6
	v_pk_add_f32 v[8:9], v[8:9], v[132:133]
	v_and_b32_e32 v135, 0xffff0000, v1
	v_lshlrev_b32_e32 v138, 16, v28
	v_and_b32_e32 v139, 0xffff0000, v28
	v_lshlrev_b32_e32 v148, 16, v23
	v_and_b32_e32 v149, 0xffff0000, v23
	v_cndmask_b32_e32 v15, 0, v15, vcc
	v_cndmask_b32_e32 v14, 0, v14, vcc
	v_div_fixup_f32 v4, v22, v35, 1.0
	v_pk_add_f32 v[6:7], v[86:87], 0 op_sel_hi:[1,0]
	v_pk_add_f32 v[136:137], v[8:9], v[134:135]
	v_pk_add_f32 v[8:9], v[138:139], 0 op_sel_hi:[1,0]
	v_lshlrev_b32_e32 v140, 16, v10
	v_and_b32_e32 v141, 0xffff0000, v10
	v_pk_add_f32 v[10:11], v[148:149], 0 op_sel_hi:[1,0]
	v_lshlrev_b32_e32 v150, 16, v29
	v_and_b32_e32 v151, 0xffff0000, v29
	v_pk_add_f32 v[6:7], v[6:7], v[106:107]
	v_lshlrev_b32_e32 v110, 16, v0
	v_and_b32_e32 v111, 0xffff0000, v0
	v_pk_fma_f32 v[0:1], v[4:5], v[136:137], v[134:135] op_sel_hi:[0,1,1] neg_lo:[0,0,1] neg_hi:[0,0,1]
	v_pk_add_f32 v[8:9], v[8:9], v[140:141]
	v_lshlrev_b32_e32 v142, 16, v14
	v_and_b32_e32 v143, 0xffff0000, v14
	v_pk_add_f32 v[10:11], v[10:11], v[150:151]
	v_lshlrev_b32_e32 v152, 16, v15
	v_and_b32_e32 v153, 0xffff0000, v15
	v_pk_add_f32 v[6:7], v[6:7], v[108:109]
	v_pk_add_f32 v[8:9], v[8:9], v[142:143]
	v_lshlrev_b32_e32 v144, 16, v2
	v_and_b32_e32 v145, 0xffff0000, v2
	v_pk_add_f32 v[10:11], v[10:11], v[152:153]
	v_lshlrev_b32_e32 v154, 16, v3
	v_and_b32_e32 v155, 0xffff0000, v3
	v_cvt_pk_bf16_f32 v91, v0, v1
	v_min_i32_e32 v0, 3, v121
	v_pk_add_f32 v[126:127], v[6:7], v[110:111]
	v_pk_add_f32 v[146:147], v[8:9], v[144:145]
	v_pk_add_f32 v[156:157], v[10:11], v[154:155]
	v_add_u32_e32 v0, 1, v0
	v_pk_fma_f32 v[6:7], v[4:5], v[126:127], v[110:111] op_sel_hi:[0,1,1] neg_lo:[0,0,1] neg_hi:[0,0,1]
	v_pk_fma_f32 v[8:9], v[4:5], v[146:147], v[144:145] op_sel_hi:[0,1,1] neg_lo:[0,0,1] neg_hi:[0,0,1]
	v_pk_fma_f32 v[2:3], v[4:5], v[156:157], v[154:155] op_sel_hi:[0,1,1] neg_lo:[0,0,1] neg_hi:[0,0,1]
	v_cvt_f32_i32_e32 v69, v0
	v_lshlrev_b64 v[0:1], 12, v[66:67]
	v_cvt_pk_bf16_f32 v90, v6, v7
	v_cvt_pk_bf16_f32 v92, v8, v9
	v_cvt_pk_bf16_f32 v93, v2, v3
	v_lshl_add_u64 v[88:89], v[62:63], 0, v[0:1]
	global_load_dwordx4 v[32:35], v[32:33], off offset:1024
	s_nop 0
	global_load_dwordx4 v[28:31], v[84:85], off offset:1024
	global_load_dwordx4 v[94:97], v[58:59], off offset:512
	global_load_dwordx4 v[20:23], v[58:59], off offset:1024
	global_load_dwordx4 v[98:101], v[56:57], off offset:512
	global_load_dwordx4 v[12:15], v[56:57], off offset:1024
	global_load_dwordx4 v[102:105], v[54:55], off offset:512
	global_load_dwordx4 v[8:11], v[54:55], off offset:1024
	s_nop 0
	global_load_dwordx4 v[56:59], v[52:53], off offset:512
	global_load_dwordx4 v[4:7], v[52:53], off offset:1024
	s_nop 0
	global_load_dwordx4 v[52:55], v[82:83], off offset:512
	global_load_dwordx4 v[0:3], v[82:83], off offset:1024
	v_div_scale_f32 v158, s[46:47], v69, v69, 1.0
	v_rcp_f32_e32 v159, v158
	global_store_dwordx4 v[88:89], v[90:93], off offset:512
	v_fma_f32 v82, -v158, v159, 1.0
	v_fmac_f32_e32 v159, v82, v159
	v_div_scale_f32 v82, vcc, 1.0, v69, 1.0
	v_mul_f32_e32 v83, v82, v159
	v_fma_f32 v84, -v158, v83, v82
	v_fmac_f32_e32 v83, v84, v159
	v_fma_f32 v82, -v158, v83, v82
	v_pk_add_f32 v[92:93], v[136:137], v[128:129] neg_lo:[0,1] neg_hi:[0,1]
	s_waitcnt vmcnt(18)
	v_lshlrev_b32_e32 v136, 16, v26
	v_and_b32_e32 v137, 0xffff0000, v26
	v_min_i32_e32 v26, 3, v120
	v_div_fmas_f32 v82, v82, v159, v83
	v_add_u32_e32 v26, 1, v26
	v_div_fixup_f32 v82, v82, v69, 1.0
	v_cvt_f32_i32_e32 v69, v26
	v_pk_add_f32 v[84:85], v[126:127], v[86:87] neg_lo:[0,1] neg_hi:[0,1]
	v_lshlrev_b32_e32 v126, 16, v25
	v_and_b32_e32 v127, 0xffff0000, v25
	v_lshlrev_b32_e32 v90, 16, v24
	v_and_b32_e32 v91, 0xffff0000, v24
	v_pk_add_f32 v[92:93], v[92:93], v[126:127]
	v_pk_add_f32 v[24:25], v[146:147], v[138:139] neg_lo:[0,1] neg_hi:[0,1]
	v_pk_fma_f32 v[128:129], v[82:83], v[92:93], v[126:127] op_sel_hi:[0,1,1] neg_lo:[0,0,1] neg_hi:[0,0,1]
	v_pk_add_f32 v[138:139], v[24:25], v[136:137]
	v_pk_add_f32 v[24:25], v[156:157], v[148:149] neg_lo:[0,1] neg_hi:[0,1]
	v_lshlrev_b32_e32 v148, 16, v27
	v_and_b32_e32 v149, 0xffff0000, v27
	v_pk_add_f32 v[156:157], v[24:25], v[148:149]
	v_cvt_pk_bf16_f32 v25, v128, v129
	v_div_scale_f32 v128, s[46:47], v69, v69, 1.0
	v_pk_add_f32 v[84:85], v[84:85], v[90:91]
	v_rcp_f32_e32 v129, v128
	v_pk_fma_f32 v[86:87], v[82:83], v[84:85], v[90:91] op_sel_hi:[0,1,1] neg_lo:[0,0,1] neg_hi:[0,0,1]
	v_pk_fma_f32 v[146:147], v[82:83], v[138:139], v[136:137] op_sel_hi:[0,1,1] neg_lo:[0,0,1] neg_hi:[0,0,1]
	v_pk_fma_f32 v[82:83], v[82:83], v[156:157], v[148:149] op_sel_hi:[0,1,1] neg_lo:[0,0,1] neg_hi:[0,0,1]
	v_cvt_pk_bf16_f32 v27, v82, v83
	v_lshlrev_b64 v[82:83], 12, v[80:81]
	v_cvt_pk_bf16_f32 v24, v86, v87
	v_cvt_pk_bf16_f32 v26, v146, v147
	v_lshl_add_u64 v[86:87], v[62:63], 0, v[82:83]
	global_store_dwordx4 v[86:87], v[24:27], off offset:512
	s_waitcnt vmcnt(18)
	v_lshlrev_b32_e32 v146, 16, v19
	v_and_b32_e32 v147, 0xffff0000, v19
	v_fma_f32 v24, -v128, v129, 1.0
	v_fmac_f32_e32 v129, v24, v129
	v_div_scale_f32 v24, vcc, 1.0, v69, 1.0
	v_mul_f32_e32 v25, v24, v129
	v_fma_f32 v26, -v128, v25, v24
	v_fmac_f32_e32 v25, v26, v129
	v_fma_f32 v24, -v128, v25, v24
	v_pk_add_f32 v[26:27], v[84:85], v[106:107] neg_lo:[0,1] neg_hi:[0,1]
	v_pk_add_f32 v[84:85], v[92:93], v[130:131] neg_lo:[0,1] neg_hi:[0,1]
	v_lshlrev_b32_e32 v130, 16, v18
	v_and_b32_e32 v131, 0xffff0000, v18
	v_min_i32_e32 v18, 3, v119
	v_div_fmas_f32 v24, v24, v129, v25
	v_add_u32_e32 v18, 1, v18
	v_div_fixup_f32 v24, v24, v69, 1.0
	v_cvt_f32_i32_e32 v69, v18
	v_lshlrev_b32_e32 v106, 16, v16
	v_and_b32_e32 v107, 0xffff0000, v16
	v_pk_add_f32 v[26:27], v[26:27], v[106:107]
	v_lshlrev_b32_e32 v128, 16, v17
	v_and_b32_e32 v129, 0xffff0000, v17
	v_pk_add_f32 v[16:17], v[138:139], v[140:141] neg_lo:[0,1] neg_hi:[0,1]
	v_pk_fma_f32 v[82:83], v[24:25], v[26:27], v[106:107] op_sel_hi:[0,1,1] neg_lo:[0,0,1] neg_hi:[0,0,1]
	v_pk_add_f32 v[138:139], v[16:17], v[130:131]
	v_pk_add_f32 v[16:17], v[156:157], v[150:151] neg_lo:[0,1] neg_hi:[0,1]
	v_pk_add_f32 v[92:93], v[84:85], v[128:129]
	v_pk_add_f32 v[150:151], v[16:17], v[146:147]
	v_cvt_pk_bf16_f32 v16, v82, v83
	v_div_scale_f32 v82, s[46:47], v69, v69, 1.0
	v_rcp_f32_e32 v83, v82
	v_pk_fma_f32 v[84:85], v[24:25], v[92:93], v[128:129] op_sel_hi:[0,1,1] neg_lo:[0,0,1] neg_hi:[0,0,1]
	v_pk_fma_f32 v[140:141], v[24:25], v[138:139], v[130:131] op_sel_hi:[0,1,1] neg_lo:[0,0,1] neg_hi:[0,0,1]
	v_pk_fma_f32 v[24:25], v[24:25], v[150:151], v[146:147] op_sel_hi:[0,1,1] neg_lo:[0,0,1] neg_hi:[0,0,1]
	v_cvt_pk_bf16_f32 v19, v24, v25
	v_lshlrev_b64 v[24:25], 12, v[78:79]
	v_cvt_pk_bf16_f32 v17, v84, v85
	v_cvt_pk_bf16_f32 v18, v140, v141
	v_lshl_add_u64 v[84:85], v[62:63], 0, v[24:25]
	global_store_dwordx4 v[84:85], v[16:19], off offset:512
	v_pk_add_f32 v[140:141], v[150:151], v[152:153] neg_lo:[0,1] neg_hi:[0,1]
	s_nop 0
	v_fma_f32 v16, -v82, v83, 1.0
	v_fmac_f32_e32 v83, v16, v83
	v_div_scale_f32 v16, vcc, 1.0, v69, 1.0
	v_mul_f32_e32 v17, v16, v83
	v_fma_f32 v18, -v82, v17, v16
	v_fmac_f32_e32 v17, v18, v83
	v_fma_f32 v16, -v82, v17, v16
	v_div_fmas_f32 v16, v16, v83, v17
	v_pk_add_f32 v[18:19], v[26:27], v[108:109] neg_lo:[0,1] neg_hi:[0,1]
	s_waitcnt vmcnt(12)
	v_lshlrev_b32_e32 v108, 16, v94
	v_and_b32_e32 v109, 0xffff0000, v94
	v_div_fixup_f32 v16, v16, v69, 1.0
	v_pk_add_f32 v[24:25], v[18:19], v[108:109]
	v_pk_add_f32 v[26:27], v[92:93], v[132:133] neg_lo:[0,1] neg_hi:[0,1]
	v_lshlrev_b32_e32 v132, 16, v95
	v_and_b32_e32 v133, 0xffff0000, v95
	v_pk_add_f32 v[92:93], v[138:139], v[142:143] neg_lo:[0,1] neg_hi:[0,1]
	v_lshlrev_b32_e32 v138, 16, v96
	v_and_b32_e32 v139, 0xffff0000, v96
	v_lshlrev_b32_e32 v142, 16, v97
	v_and_b32_e32 v143, 0xffff0000, v97
	v_pk_fma_f32 v[18:19], v[16:17], v[24:25], v[108:109] op_sel_hi:[0,1,1] neg_lo:[0,0,1] neg_hi:[0,0,1]
	v_pk_add_f32 v[26:27], v[26:27], v[132:133]
	v_pk_add_f32 v[92:93], v[92:93], v[138:139]
	v_pk_add_f32 v[96:97], v[140:141], v[142:143]
	v_pk_fma_f32 v[82:83], v[16:17], v[26:27], v[132:133] op_sel_hi:[0,1,1] neg_lo:[0,0,1] neg_hi:[0,0,1]
	v_pk_fma_f32 v[94:95], v[16:17], v[92:93], v[138:139] op_sel_hi:[0,1,1] neg_lo:[0,0,1] neg_hi:[0,0,1]
	v_pk_fma_f32 v[140:141], v[16:17], v[96:97], v[142:143] op_sel_hi:[0,1,1] neg_lo:[0,0,1] neg_hi:[0,0,1]
	v_cvt_pk_bf16_f32 v16, v18, v19
	v_min_i32_e32 v18, 3, v118
	v_add_u32_e32 v18, 1, v18
	v_cvt_f32_i32_e32 v69, v18
	v_cvt_pk_bf16_f32 v18, v94, v95
	v_cvt_pk_bf16_f32 v17, v82, v83
	v_lshlrev_b64 v[82:83], 12, v[76:77]
	v_div_scale_f32 v94, s[46:47], v69, v69, 1.0
	v_rcp_f32_e32 v95, v94
	v_cvt_pk_bf16_f32 v19, v140, v141
	v_lshl_add_u64 v[82:83], v[62:63], 0, v[82:83]
	global_store_dwordx4 v[82:83], v[16:19], off offset:512
	v_pk_add_f32 v[92:93], v[92:93], v[144:145] neg_lo:[0,1] neg_hi:[0,1]
	v_pk_add_f32 v[96:97], v[96:97], v[154:155] neg_lo:[0,1] neg_hi:[0,1]
	v_fma_f32 v16, -v94, v95, 1.0
	v_fmac_f32_e32 v95, v16, v95
	v_div_scale_f32 v16, vcc, 1.0, v69, 1.0
	v_mul_f32_e32 v17, v16, v95
	v_fma_f32 v18, -v94, v17, v16
	v_fmac_f32_e32 v17, v18, v95
	v_fma_f32 v16, -v94, v17, v16
	v_div_fmas_f32 v16, v16, v95, v17
	v_pk_add_f32 v[18:19], v[24:25], v[110:111] neg_lo:[0,1] neg_hi:[0,1]
	s_waitcnt vmcnt(11)
	v_lshlrev_b32_e32 v24, 16, v98
	v_and_b32_e32 v25, 0xffff0000, v98
	v_div_fixup_f32 v16, v16, v69, 1.0
	v_pk_add_f32 v[94:95], v[18:19], v[24:25]
	v_lshlrev_b32_e32 v98, 16, v100
	v_pk_fma_f32 v[18:19], v[16:17], v[94:95], v[24:25] op_sel_hi:[0,1,1] neg_lo:[0,0,1] neg_hi:[0,0,1]
	v_pk_add_f32 v[24:25], v[26:27], v[134:135] neg_lo:[0,1] neg_hi:[0,1]
	v_lshlrev_b32_e32 v26, 16, v99
	v_and_b32_e32 v27, 0xffff0000, v99
	v_and_b32_e32 v99, 0xffff0000, v100
	v_lshlrev_b32_e32 v100, 16, v101
	v_and_b32_e32 v101, 0xffff0000, v101
	v_pk_add_f32 v[24:25], v[24:25], v[26:27]
	v_pk_add_f32 v[92:93], v[92:93], v[98:99]
	v_pk_add_f32 v[96:97], v[96:97], v[100:101]
	v_pk_fma_f32 v[26:27], v[16:17], v[24:25], v[26:27] op_sel_hi:[0,1,1] neg_lo:[0,0,1] neg_hi:[0,0,1]
	v_pk_fma_f32 v[98:99], v[16:17], v[92:93], v[98:99] op_sel_hi:[0,1,1] neg_lo:[0,0,1] neg_hi:[0,0,1]
	v_pk_fma_f32 v[100:101], v[16:17], v[96:97], v[100:101] op_sel_hi:[0,1,1] neg_lo:[0,0,1] neg_hi:[0,0,1]
	v_cvt_pk_bf16_f32 v16, v18, v19
	v_min_i32_e32 v18, 3, v117
	v_add_u32_e32 v18, 1, v18
	v_cvt_f32_i32_e32 v69, v18
	v_cvt_pk_bf16_f32 v18, v98, v99
	v_cvt_pk_bf16_f32 v17, v26, v27
	v_lshlrev_b64 v[26:27], 12, v[74:75]
	v_div_scale_f32 v98, s[46:47], v69, v69, 1.0
	v_rcp_f32_e32 v99, v98
	v_cvt_pk_bf16_f32 v19, v100, v101
	v_lshl_add_u64 v[26:27], v[62:63], 0, v[26:27]
	global_store_dwordx4 v[26:27], v[16:19], off offset:512
	v_pk_add_f32 v[24:25], v[24:25], v[126:127] neg_lo:[0,1] neg_hi:[0,1]
	s_nop 0
	v_fma_f32 v16, -v98, v99, 1.0
	v_fmac_f32_e32 v99, v16, v99
	v_div_scale_f32 v16, vcc, 1.0, v69, 1.0
	v_mul_f32_e32 v17, v16, v99
	v_fma_f32 v18, -v98, v17, v16
	v_fmac_f32_e32 v17, v18, v99
	v_fma_f32 v16, -v98, v17, v16
	v_div_fmas_f32 v16, v16, v99, v17
	v_pk_add_f32 v[18:19], v[94:95], v[90:91] neg_lo:[0,1] neg_hi:[0,1]
	s_waitcnt vmcnt(10)
	v_lshlrev_b32_e32 v90, 16, v102
	v_and_b32_e32 v91, 0xffff0000, v102
	v_div_fixup_f32 v16, v16, v69, 1.0
	v_pk_add_f32 v[94:95], v[18:19], v[90:91]
	s_nop 0
	v_pk_fma_f32 v[18:19], v[16:17], v[94:95], v[90:91] op_sel_hi:[0,1,1] neg_lo:[0,0,1] neg_hi:[0,0,1]
	v_lshlrev_b32_e32 v90, 16, v103
	v_and_b32_e32 v91, 0xffff0000, v103
	v_pk_add_f32 v[24:25], v[24:25], v[90:91]
	s_nop 0
	v_pk_fma_f32 v[98:99], v[16:17], v[24:25], v[90:91] op_sel_hi:[0,1,1] neg_lo:[0,0,1] neg_hi:[0,0,1]
	v_pk_add_f32 v[90:91], v[92:93], v[136:137] neg_lo:[0,1] neg_hi:[0,1]
	v_lshlrev_b32_e32 v92, 16, v104
	v_and_b32_e32 v93, 0xffff0000, v104
	v_pk_add_f32 v[110:111], v[90:91], v[92:93]
	v_pk_add_f32 v[90:91], v[96:97], v[148:149] neg_lo:[0,1] neg_hi:[0,1]
	v_lshlrev_b32_e32 v96, 16, v105
	v_and_b32_e32 v97, 0xffff0000, v105
	v_pk_add_f32 v[126:127], v[90:91], v[96:97]
	v_cvt_pk_bf16_f32 v90, v18, v19
	v_min_i32_e32 v18, 3, v116
	v_add_u32_e32 v18, 1, v18
	v_cvt_f32_i32_e32 v69, v18
	v_pk_fma_f32 v[92:93], v[16:17], v[110:111], v[92:93] op_sel_hi:[0,1,1] neg_lo:[0,0,1] neg_hi:[0,0,1]
	v_pk_fma_f32 v[16:17], v[16:17], v[126:127], v[96:97] op_sel_hi:[0,1,1] neg_lo:[0,0,1] neg_hi:[0,0,1]
	v_cvt_pk_bf16_f32 v92, v92, v93
	v_div_scale_f32 v96, s[46:47], v69, v69, 1.0
	v_rcp_f32_e32 v97, v96
	v_cvt_pk_bf16_f32 v93, v16, v17
	v_lshlrev_b64 v[16:17], 12, v[72:73]
	v_lshl_add_u64 v[18:19], v[62:63], 0, v[16:17]
	v_fma_f32 v16, -v96, v97, 1.0
	v_fmac_f32_e32 v97, v16, v97
	v_div_scale_f32 v16, vcc, 1.0, v69, 1.0
	v_cvt_pk_bf16_f32 v91, v98, v99
	v_mul_f32_e32 v17, v16, v97
	global_store_dwordx4 v[18:19], v[90:93], off offset:512
	v_pk_add_f32 v[24:25], v[24:25], v[128:129] neg_lo:[0,1] neg_hi:[0,1]
	v_add_u32_e32 v136, -7, v66
	v_fma_f32 v90, -v96, v17, v16
	v_fmac_f32_e32 v17, v90, v97
	v_fma_f32 v16, -v96, v17, v16
	v_div_fmas_f32 v16, v16, v97, v17
	s_waitcnt vmcnt(9)
	v_lshlrev_b32_e32 v92, 16, v56
	v_and_b32_e32 v93, 0xffff0000, v56
	v_lshlrev_b32_e32 v56, 16, v57
	v_and_b32_e32 v57, 0xffff0000, v57
	v_div_fixup_f32 v16, v16, v69, 1.0
	v_pk_add_f32 v[128:129], v[24:25], v[56:57]
	v_pk_add_f32 v[90:91], v[94:95], v[106:107] neg_lo:[0,1] neg_hi:[0,1]
	v_pk_fma_f32 v[24:25], v[16:17], v[128:129], v[56:57] op_sel_hi:[0,1,1] neg_lo:[0,0,1] neg_hi:[0,0,1]
	v_max_i32_e32 v56, s8, v136
	v_ashrrev_i32_e32 v57, 31, v56
	v_pk_add_f32 v[106:107], v[90:91], v[92:93]
	v_lshlrev_b64 v[56:57], 12, v[56:57]
	v_pk_fma_f32 v[134:135], v[16:17], v[106:107], v[92:93] op_sel_hi:[0,1,1] neg_lo:[0,0,1] neg_hi:[0,0,1]
	v_lshl_add_u64 v[56:57], v[64:65], 0, v[56:57]
	v_add_u32_e32 v17, -6, v66
	global_load_dwordx4 v[90:93], v[56:57], off offset:1024
	v_max_i32_e32 v56, s8, v17
	v_ashrrev_i32_e32 v57, 31, v56
	v_lshlrev_b64 v[56:57], 12, v[56:57]
	v_lshl_add_u64 v[56:57], v[64:65], 0, v[56:57]
	v_add_u32_e32 v17, -5, v66
	global_load_dwordx4 v[94:97], v[56:57], off offset:1024
	v_max_i32_e32 v56, s8, v17
	v_ashrrev_i32_e32 v57, 31, v56
	v_lshlrev_b64 v[56:57], 12, v[56:57]
	v_lshl_add_u64 v[56:57], v[64:65], 0, v[56:57]
	v_add_u32_e32 v17, -4, v66
	global_load_dwordx4 v[98:101], v[56:57], off offset:1024
	v_max_i32_e32 v56, s8, v17
	v_ashrrev_i32_e32 v57, 31, v56
	v_lshlrev_b64 v[56:57], 12, v[56:57]
	v_lshl_add_u64 v[56:57], v[64:65], 0, v[56:57]
	global_load_dwordx4 v[102:105], v[56:57], off offset:1024
	v_pk_add_f32 v[56:57], v[110:111], v[130:131] neg_lo:[0,1] neg_hi:[0,1]
	v_lshlrev_b32_e32 v110, 16, v58
	v_and_b32_e32 v111, 0xffff0000, v58
	v_pk_add_f32 v[130:131], v[56:57], v[110:111]
	v_pk_add_f32 v[56:57], v[126:127], v[146:147] neg_lo:[0,1] neg_hi:[0,1]
	v_lshlrev_b32_e32 v58, 16, v59
	v_and_b32_e32 v59, 0xffff0000, v59
	v_pk_add_f32 v[126:127], v[56:57], v[58:59]
	v_cvt_pk_bf16_f32 v57, v24, v25
	v_min_i32_e32 v24, 3, v60
	v_add_u32_e32 v24, 1, v24
	v_cvt_f32_i32_e32 v69, v24
	v_pk_fma_f32 v[110:111], v[16:17], v[130:131], v[110:111] op_sel_hi:[0,1,1] neg_lo:[0,0,1] neg_hi:[0,0,1]
	v_pk_fma_f32 v[16:17], v[16:17], v[126:127], v[58:59] op_sel_hi:[0,1,1] neg_lo:[0,0,1] neg_hi:[0,0,1]
	v_cvt_pk_bf16_f32 v58, v110, v111
	v_div_scale_f32 v110, s[8:9], v69, v69, 1.0
	v_rcp_f32_e32 v111, v110
	v_cvt_pk_bf16_f32 v59, v16, v17
	v_lshlrev_b64 v[16:17], 12, v[70:71]
	v_lshl_add_u64 v[24:25], v[62:63], 0, v[16:17]
	v_fma_f32 v16, -v110, v111, 1.0
	v_fmac_f32_e32 v111, v16, v111
	v_div_scale_f32 v16, vcc, 1.0, v69, 1.0
	v_cvt_pk_bf16_f32 v56, v134, v135
	v_mul_f32_e32 v17, v16, v111
	global_store_dwordx4 v[24:25], v[56:59], off offset:512
	s_nop 1
	v_fma_f32 v56, -v110, v17, v16
	v_fmac_f32_e32 v17, v56, v111
	v_fma_f32 v16, -v110, v17, v16
	v_div_fmas_f32 v16, v16, v111, v17
	v_pk_add_f32 v[56:57], v[106:107], v[108:109] neg_lo:[0,1] neg_hi:[0,1]
	s_waitcnt vmcnt(12)
	v_lshlrev_b32_e32 v58, 16, v52
	v_and_b32_e32 v59, 0xffff0000, v52
	v_div_fixup_f32 v16, v16, v69, 1.0
	v_pk_add_f32 v[56:57], v[56:57], v[58:59]
	v_lshlrev_b32_e32 v52, 16, v53
	v_pk_fma_f32 v[56:57], v[16:17], v[56:57], v[58:59] op_sel_hi:[0,1,1] neg_lo:[0,0,1] neg_hi:[0,0,1]
	v_pk_add_f32 v[58:59], v[128:129], v[132:133] neg_lo:[0,1] neg_hi:[0,1]
	v_and_b32_e32 v53, 0xffff0000, v53
	v_pk_add_f32 v[58:59], v[58:59], v[52:53]
	v_lshlrev_b32_e32 v106, 16, v54
	v_pk_fma_f32 v[58:59], v[16:17], v[58:59], v[52:53] op_sel_hi:[0,1,1] neg_lo:[0,0,1] neg_hi:[0,0,1]
	v_pk_add_f32 v[52:53], v[130:131], v[138:139] neg_lo:[0,1] neg_hi:[0,1]
	v_and_b32_e32 v107, 0xffff0000, v54
	v_pk_add_f32 v[52:53], v[52:53], v[106:107]
	v_lshlrev_b32_e32 v54, 16, v55
	v_pk_fma_f32 v[106:107], v[16:17], v[52:53], v[106:107] op_sel_hi:[0,1,1] neg_lo:[0,0,1] neg_hi:[0,0,1]
	v_pk_add_f32 v[52:53], v[126:127], v[142:143] neg_lo:[0,1] neg_hi:[0,1]
	v_and_b32_e32 v55, 0xffff0000, v55
	v_pk_add_f32 v[52:53], v[52:53], v[54:55]
	v_ashrrev_i32_e32 v69, 31, v68
	v_pk_fma_f32 v[16:17], v[16:17], v[52:53], v[54:55] op_sel_hi:[0,1,1] neg_lo:[0,0,1] neg_hi:[0,0,1]
	v_cvt_pk_bf16_f32 v55, v16, v17
	v_lshlrev_b64 v[16:17], 12, v[68:69]
	v_cvt_pk_bf16_f32 v52, v56, v57
	v_cvt_pk_bf16_f32 v53, v58, v59
	v_cvt_pk_bf16_f32 v54, v106, v107
	v_lshl_add_u64 v[16:17], v[62:63], 0, v[16:17]
	global_store_dwordx4 v[16:17], v[52:55], off offset:512
	s_nop 1
	v_add_u32_e32 v52, s10, v136
	v_cmp_lt_i32_e32 vcc, -1, v52
	s_waitcnt vmcnt(5)
	s_nop 0
	v_cndmask_b32_e32 v53, 0, v93, vcc
	v_cndmask_b32_e32 v54, 0, v92, vcc
	v_cndmask_b32_e32 v55, 0, v91, vcc
	v_cndmask_b32_e32 v56, 0, v90, vcc
	v_cmp_lt_i32_e32 vcc, -2, v52
	v_lshlrev_b32_e32 v130, 16, v56
	v_and_b32_e32 v131, 0xffff0000, v56
	s_waitcnt vmcnt(4)
	v_cndmask_b32_e32 v57, 0, v97, vcc
	v_cndmask_b32_e32 v58, 0, v96, vcc
	v_cndmask_b32_e32 v59, 0, v95, vcc
	v_cndmask_b32_e32 v69, 0, v94, vcc
	v_cmp_lt_i32_e32 vcc, -3, v52
	v_lshlrev_b32_e32 v106, 16, v69
	v_and_b32_e32 v107, 0xffff0000, v69
	s_waitcnt vmcnt(3)
	v_cndmask_b32_e32 v94, 0, v101, vcc
	v_cndmask_b32_e32 v90, 0, v100, vcc
	v_cndmask_b32_e32 v91, 0, v99, vcc
	v_cndmask_b32_e32 v92, 0, v98, vcc
	v_cmp_lt_i32_e32 vcc, -4, v52
	v_lshlrev_b32_e32 v96, 16, v92
	v_and_b32_e32 v97, 0xffff0000, v92
	s_waitcnt vmcnt(2)
	v_cndmask_b32_e32 v95, 0, v105, vcc
	v_cndmask_b32_e32 v99, 0, v104, vcc
	v_cndmask_b32_e32 v93, 0, v103, vcc
	v_cndmask_b32_e32 v98, 0, v102, vcc
	v_cmp_lt_i32_e32 vcc, -5, v52
	v_lshlrev_b32_e32 v102, 16, v59
	v_and_b32_e32 v103, 0xffff0000, v59
	v_cndmask_b32_e32 v127, 0, v51, vcc
	v_cndmask_b32_e32 v110, 0, v50, vcc
	v_cndmask_b32_e32 v49, 0, v49, vcc
	v_cndmask_b32_e32 v48, 0, v48, vcc
	v_cmp_lt_i32_e32 vcc, -6, v52
	v_lshlrev_b32_e32 v104, 16, v58
	v_and_b32_e32 v105, 0xffff0000, v58
	v_cndmask_b32_e32 v152, 0, v47, vcc
	v_cndmask_b32_e32 v111, 0, v46, vcc
	v_cndmask_b32_e32 v140, 0, v45, vcc
	v_cndmask_b32_e32 v45, 0, v44, vcc
	v_cmp_lt_i32_e32 vcc, -7, v52
	v_lshlrev_b32_e32 v58, 16, v98
	v_and_b32_e32 v59, 0xffff0000, v98
	v_cndmask_b32_e32 v46, 0, v40, vcc
	v_min_i32_e32 v40, 7, v122
	v_add_u32_e32 v40, 1, v40
	v_cvt_f32_i32_e32 v40, v40
	v_cndmask_b32_e32 v52, 0, v41, vcc
	v_cndmask_b32_e32 v146, 0, v42, vcc
	v_cndmask_b32_e32 v154, 0, v43, vcc
	v_div_scale_f32 v41, s[8:9], v40, v40, 1.0
	v_rcp_f32_e32 v42, v41
	v_lshlrev_b32_e32 v50, 16, v48
	v_and_b32_e32 v51, 0xffff0000, v48
	v_lshlrev_b32_e32 v132, 16, v55
	v_fma_f32 v43, -v41, v42, 1.0
	v_fmac_f32_e32 v42, v43, v42
	v_div_scale_f32 v43, vcc, 1.0, v40, 1.0
	v_mul_f32_e32 v44, v43, v42
	v_fma_f32 v47, -v41, v44, v43
	v_fmac_f32_e32 v44, v47, v42
	v_fma_f32 v41, -v41, v44, v43
	v_div_fmas_f32 v41, v41, v42, v44
	v_div_fixup_f32 v126, v41, v40, 1.0
	v_pk_add_f32 v[40:41], v[130:131], 0 op_sel_hi:[1,0]
	v_lshlrev_b32_e32 v44, 16, v45
	v_pk_add_f32 v[40:41], v[40:41], v[106:107]
	v_and_b32_e32 v45, 0xffff0000, v45
	v_pk_add_f32 v[40:41], v[40:41], v[96:97]
	v_and_b32_e32 v133, 0xffff0000, v55
	v_pk_add_f32 v[40:41], v[40:41], v[58:59]
	v_and_b32_e32 v47, 0xffff0000, v36
	v_pk_add_f32 v[40:41], v[40:41], v[50:51]
	v_lshlrev_b32_e32 v108, 16, v91
	v_pk_add_f32 v[42:43], v[40:41], v[44:45]
	v_lshlrev_b32_e32 v40, 16, v46
	v_and_b32_e32 v41, 0xffff0000, v46
	v_pk_add_f32 v[42:43], v[42:43], v[40:41]
	v_lshlrev_b32_e32 v46, 16, v36
	v_pk_add_f32 v[138:139], v[42:43], v[46:47]
	v_pk_add_f32 v[42:43], v[132:133], 0 op_sel_hi:[1,0]
	v_and_b32_e32 v109, 0xffff0000, v91
	v_pk_add_f32 v[42:43], v[42:43], v[102:103]
	v_lshlrev_b32_e32 v92, 16, v93
	v_pk_add_f32 v[42:43], v[42:43], v[108:109]
	v_and_b32_e32 v93, 0xffff0000, v93
	v_lshlrev_b32_e32 v134, 16, v54
	v_and_b32_e32 v135, 0xffff0000, v54
	v_pk_add_f32 v[42:43], v[42:43], v[92:93]
	v_lshlrev_b32_e32 v54, 16, v49
	v_and_b32_e32 v55, 0xffff0000, v49
	v_pk_fma_f32 v[128:129], v[126:127], v[138:139], v[46:47] op_sel_hi:[0,1,1] neg_lo:[0,0,1] neg_hi:[0,0,1]
	v_pk_add_f32 v[42:43], v[42:43], v[54:55]
	v_lshlrev_b32_e32 v46, 16, v140
	v_and_b32_e32 v47, 0xffff0000, v140
	v_pk_add_f32 v[48:49], v[42:43], v[46:47]
	v_lshlrev_b32_e32 v42, 16, v52
	v_and_b32_e32 v43, 0xffff0000, v52
	v_pk_add_f32 v[48:49], v[48:49], v[42:43]
	v_lshlrev_b32_e32 v36, 16, v37
	v_and_b32_e32 v37, 0xffff0000, v37
	v_pk_add_f32 v[140:141], v[48:49], v[36:37]
	v_lshlrev_b32_e32 v144, 16, v90
	v_pk_fma_f32 v[142:143], v[126:127], v[140:141], v[36:37] op_sel_hi:[0,1,1] neg_lo:[0,0,1] neg_hi:[0,0,1]
	v_pk_add_f32 v[36:37], v[134:135], 0 op_sel_hi:[1,0]
	v_and_b32_e32 v145, 0xffff0000, v90
	v_pk_add_f32 v[36:37], v[36:37], v[104:105]
	v_lshlrev_b32_e32 v98, 16, v99
	v_pk_add_f32 v[36:37], v[36:37], v[144:145]
	v_and_b32_e32 v99, 0xffff0000, v99
	v_pk_add_f32 v[36:37], v[36:37], v[98:99]
	v_lshlrev_b32_e32 v90, 16, v110
	v_and_b32_e32 v91, 0xffff0000, v110
	v_lshlrev_b32_e32 v136, 16, v53
	v_and_b32_e32 v137, 0xffff0000, v53
	v_pk_add_f32 v[36:37], v[36:37], v[90:91]
	v_lshlrev_b32_e32 v52, 16, v111
	v_and_b32_e32 v53, 0xffff0000, v111
	v_pk_add_f32 v[48:49], v[36:37], v[52:53]
	v_lshlrev_b32_e32 v36, 16, v146
	v_and_b32_e32 v37, 0xffff0000, v146
	v_lshlrev_b32_e32 v100, 16, v57
	v_and_b32_e32 v101, 0xffff0000, v57
	v_pk_add_f32 v[48:49], v[48:49], v[36:37]
	v_lshlrev_b32_e32 v56, 16, v38
	v_and_b32_e32 v57, 0xffff0000, v38
	v_pk_add_f32 v[146:147], v[48:49], v[56:57]
	v_pk_add_f32 v[48:49], v[136:137], 0 op_sel_hi:[1,0]
	v_lshlrev_b32_e32 v150, 16, v94
	v_pk_add_f32 v[48:49], v[48:49], v[100:101]
	v_and_b32_e32 v151, 0xffff0000, v94
	v_pk_add_f32 v[48:49], v[48:49], v[150:151]
	v_lshlrev_b32_e32 v110, 16, v95
	v_and_b32_e32 v111, 0xffff0000, v95
	v_min_i32_e32 v69, 7, v121
	v_pk_add_f32 v[48:49], v[48:49], v[110:111]
	v_lshlrev_b32_e32 v94, 16, v127
	v_and_b32_e32 v95, 0xffff0000, v127
	v_add_u32_e32 v69, 1, v69
	v_pk_fma_f32 v[148:149], v[126:127], v[146:147], v[56:57] op_sel_hi:[0,1,1] neg_lo:[0,0,1] neg_hi:[0,0,1]
	v_pk_add_f32 v[48:49], v[48:49], v[94:95]
	v_lshlrev_b32_e32 v56, 16, v152
	v_and_b32_e32 v57, 0xffff0000, v152
	v_cvt_f32_i32_e32 v69, v69
	v_pk_add_f32 v[152:153], v[48:49], v[56:57]
	v_lshlrev_b32_e32 v48, 16, v154
	v_and_b32_e32 v49, 0xffff0000, v154
	v_pk_add_f32 v[152:153], v[152:153], v[48:49]
	v_lshlrev_b32_e32 v38, 16, v39
	v_and_b32_e32 v39, 0xffff0000, v39
	v_pk_add_f32 v[152:153], v[152:153], v[38:39]
	s_nop 0
	v_pk_fma_f32 v[38:39], v[126:127], v[152:153], v[38:39] op_sel_hi:[0,1,1] neg_lo:[0,0,1] neg_hi:[0,0,1]
	v_cvt_pk_bf16_f32 v127, v142, v143
	v_div_scale_f32 v142, s[8:9], v69, v69, 1.0
	v_rcp_f32_e32 v143, v142
	v_cvt_pk_bf16_f32 v126, v128, v129
	v_cvt_pk_bf16_f32 v129, v38, v39
	v_cvt_pk_bf16_f32 v128, v148, v149
	v_fma_f32 v38, -v142, v143, 1.0
	v_fmac_f32_e32 v143, v38, v143
	v_div_scale_f32 v38, vcc, 1.0, v69, 1.0
	v_mul_f32_e32 v39, v38, v143
	global_store_dwordx4 v[88:89], v[126:129], off offset:1024
	v_fma_f32 v88, -v142, v39, v38
	v_fmac_f32_e32 v39, v88, v143
	v_fma_f32 v38, -v142, v39, v38
	v_div_fmas_f32 v38, v38, v143, v39
	v_lshlrev_b32_e32 v126, 16, v32
	v_and_b32_e32 v127, 0xffff0000, v32
	v_pk_add_f32 v[128:129], v[140:141], v[132:133] neg_lo:[0,1] neg_hi:[0,1]
	v_lshlrev_b32_e32 v32, 16, v33
	v_and_b32_e32 v33, 0xffff0000, v33
	v_div_fixup_f32 v38, v38, v69, 1.0
	v_pk_add_f32 v[128:129], v[128:129], v[32:33]
	v_pk_add_f32 v[88:89], v[138:139], v[130:131] neg_lo:[0,1] neg_hi:[0,1]
	v_pk_fma_f32 v[130:131], v[38:39], v[128:129], v[32:33] op_sel_hi:[0,1,1] neg_lo:[0,0,1] neg_hi:[0,0,1]
	v_pk_add_f32 v[32:33], v[146:147], v[134:135] neg_lo:[0,1] neg_hi:[0,1]
	v_lshlrev_b32_e32 v132, 16, v34
	v_and_b32_e32 v133, 0xffff0000, v34
	v_pk_add_f32 v[134:135], v[32:33], v[132:133]
	v_pk_add_f32 v[32:33], v[152:153], v[136:137] neg_lo:[0,1] neg_hi:[0,1]
	v_lshlrev_b32_e32 v34, 16, v35
	v_and_b32_e32 v35, 0xffff0000, v35
	v_pk_add_f32 v[136:137], v[32:33], v[34:35]
	v_min_i32_e32 v32, 7, v120
	v_add_u32_e32 v32, 1, v32
	v_cvt_f32_i32_e32 v69, v32
	v_pk_add_f32 v[88:89], v[88:89], v[126:127]
	v_pk_fma_f32 v[132:133], v[38:39], v[134:135], v[132:133] op_sel_hi:[0,1,1] neg_lo:[0,0,1] neg_hi:[0,0,1]
	v_pk_fma_f32 v[126:127], v[38:39], v[88:89], v[126:127] op_sel_hi:[0,1,1] neg_lo:[0,0,1] neg_hi:[0,0,1]
	v_cvt_pk_bf16_f32 v32, v126, v127
	v_div_scale_f32 v126, s[8:9], v69, v69, 1.0
	v_rcp_f32_e32 v127, v126
	v_pk_fma_f32 v[38:39], v[38:39], v[136:137], v[34:35] op_sel_hi:[0,1,1] neg_lo:[0,0,1] neg_hi:[0,0,1]
	v_cvt_pk_bf16_f32 v33, v130, v131
	v_cvt_pk_bf16_f32 v34, v132, v133
	v_cvt_pk_bf16_f32 v35, v38, v39
	global_store_dwordx4 v[86:87], v[32:35], off offset:1024
	v_lshlrev_b32_e32 v38, 16, v28
	v_and_b32_e32 v39, 0xffff0000, v28
	v_fma_f32 v32, -v126, v127, 1.0
	v_fmac_f32_e32 v127, v32, v127
	v_div_scale_f32 v32, vcc, 1.0, v69, 1.0
	v_mul_f32_e32 v33, v32, v127
	v_fma_f32 v34, -v126, v33, v32
	v_fmac_f32_e32 v33, v34, v127
	v_fma_f32 v32, -v126, v33, v32
	v_div_fmas_f32 v32, v32, v127, v33
	v_pk_add_f32 v[86:87], v[128:129], v[102:103] neg_lo:[0,1] neg_hi:[0,1]
	v_lshlrev_b32_e32 v28, 16, v29
	v_and_b32_e32 v29, 0xffff0000, v29
	v_div_fixup_f32 v32, v32, v69, 1.0
	v_pk_add_f32 v[86:87], v[86:87], v[28:29]
	v_pk_add_f32 v[34:35], v[88:89], v[106:107] neg_lo:[0,1] neg_hi:[0,1]
	v_pk_fma_f32 v[88:89], v[32:33], v[86:87], v[28:29] op_sel_hi:[0,1,1] neg_lo:[0,0,1] neg_hi:[0,0,1]
	v_pk_add_f32 v[28:29], v[134:135], v[104:105] neg_lo:[0,1] neg_hi:[0,1]
	v_lshlrev_b32_e32 v102, 16, v30
	v_and_b32_e32 v103, 0xffff0000, v30
	v_pk_add_f32 v[104:105], v[28:29], v[102:103]
	v_pk_add_f32 v[28:29], v[136:137], v[100:101] neg_lo:[0,1] neg_hi:[0,1]
	v_lshlrev_b32_e32 v30, 16, v31
	v_and_b32_e32 v31, 0xffff0000, v31
	v_pk_add_f32 v[100:101], v[28:29], v[30:31]
	v_min_i32_e32 v28, 7, v119
	v_add_u32_e32 v28, 1, v28
	v_cvt_f32_i32_e32 v69, v28
	v_pk_add_f32 v[34:35], v[34:35], v[38:39]
	v_pk_fma_f32 v[102:103], v[32:33], v[104:105], v[102:103] op_sel_hi:[0,1,1] neg_lo:[0,0,1] neg_hi:[0,0,1]
	v_pk_fma_f32 v[38:39], v[32:33], v[34:35], v[38:39] op_sel_hi:[0,1,1] neg_lo:[0,0,1] neg_hi:[0,0,1]
	v_cvt_pk_bf16_f32 v28, v38, v39
	v_div_scale_f32 v38, s[8:9], v69, v69, 1.0
	v_rcp_f32_e32 v39, v38
	v_pk_fma_f32 v[32:33], v[32:33], v[100:101], v[30:31] op_sel_hi:[0,1,1] neg_lo:[0,0,1] neg_hi:[0,0,1]
	v_cvt_pk_bf16_f32 v29, v88, v89
	v_cvt_pk_bf16_f32 v30, v102, v103
	v_cvt_pk_bf16_f32 v31, v32, v33
	global_store_dwordx4 v[84:85], v[28:31], off offset:1024
	v_lshlrev_b32_e32 v32, 16, v20
	v_and_b32_e32 v33, 0xffff0000, v20
	v_fma_f32 v28, -v38, v39, 1.0
	v_fmac_f32_e32 v39, v28, v39
	v_div_scale_f32 v28, vcc, 1.0, v69, 1.0
	v_mul_f32_e32 v29, v28, v39
	v_fma_f32 v30, -v38, v29, v28
	v_fmac_f32_e32 v29, v30, v39
	v_fma_f32 v28, -v38, v29, v28
	v_div_fmas_f32 v28, v28, v39, v29
	v_pk_add_f32 v[30:31], v[34:35], v[96:97] neg_lo:[0,1] neg_hi:[0,1]
	v_pk_add_f32 v[34:35], v[86:87], v[108:109] neg_lo:[0,1] neg_hi:[0,1]
	v_lshlrev_b32_e32 v20, 16, v21
	v_and_b32_e32 v21, 0xffff0000, v21
	v_div_fixup_f32 v28, v28, v69, 1.0
	v_pk_add_f32 v[34:35], v[34:35], v[20:21]
	v_lshlrev_b32_e32 v84, 16, v22
	v_pk_fma_f32 v[38:39], v[28:29], v[34:35], v[20:21] op_sel_hi:[0,1,1] neg_lo:[0,0,1] neg_hi:[0,0,1]
	v_pk_add_f32 v[20:21], v[104:105], v[144:145] neg_lo:[0,1] neg_hi:[0,1]
	v_and_b32_e32 v85, 0xffff0000, v22
	v_pk_add_f32 v[86:87], v[20:21], v[84:85]
	v_pk_add_f32 v[20:21], v[100:101], v[150:151] neg_lo:[0,1] neg_hi:[0,1]
	v_lshlrev_b32_e32 v22, 16, v23
	v_and_b32_e32 v23, 0xffff0000, v23
	v_pk_add_f32 v[88:89], v[20:21], v[22:23]
	v_min_i32_e32 v20, 7, v118
	v_add_u32_e32 v20, 1, v20
	v_cvt_f32_i32_e32 v69, v20
	v_pk_add_f32 v[30:31], v[30:31], v[32:33]
	v_pk_fma_f32 v[84:85], v[28:29], v[86:87], v[84:85] op_sel_hi:[0,1,1] neg_lo:[0,0,1] neg_hi:[0,0,1]
	v_pk_fma_f32 v[32:33], v[28:29], v[30:31], v[32:33] op_sel_hi:[0,1,1] neg_lo:[0,0,1] neg_hi:[0,0,1]
	v_cvt_pk_bf16_f32 v20, v32, v33
	v_div_scale_f32 v32, s[8:9], v69, v69, 1.0
	v_rcp_f32_e32 v33, v32
	v_pk_fma_f32 v[28:29], v[28:29], v[88:89], v[22:23] op_sel_hi:[0,1,1] neg_lo:[0,0,1] neg_hi:[0,0,1]
	v_cvt_pk_bf16_f32 v21, v38, v39
	v_cvt_pk_bf16_f32 v22, v84, v85
	v_cvt_pk_bf16_f32 v23, v28, v29
	global_store_dwordx4 v[82:83], v[20:23], off offset:1024
	v_lshlrev_b32_e32 v28, 16, v12
	v_and_b32_e32 v29, 0xffff0000, v12
	v_fma_f32 v20, -v32, v33, 1.0
	v_fmac_f32_e32 v33, v20, v33
	v_div_scale_f32 v20, vcc, 1.0, v69, 1.0
	v_mul_f32_e32 v21, v20, v33
	v_fma_f32 v22, -v32, v21, v20
	v_fmac_f32_e32 v21, v22, v33
	v_fma_f32 v20, -v32, v21, v20
	v_div_fmas_f32 v20, v20, v33, v21
	v_pk_add_f32 v[22:23], v[30:31], v[58:59] neg_lo:[0,1] neg_hi:[0,1]
	v_pk_add_f32 v[30:31], v[34:35], v[92:93] neg_lo:[0,1] neg_hi:[0,1]
	v_lshlrev_b32_e32 v12, 16, v13
	v_and_b32_e32 v13, 0xffff0000, v13
	v_div_fixup_f32 v20, v20, v69, 1.0
	v_pk_add_f32 v[30:31], v[30:31], v[12:13]
	v_lshlrev_b32_e32 v34, 16, v14
	v_pk_fma_f32 v[32:33], v[20:21], v[30:31], v[12:13] op_sel_hi:[0,1,1] neg_lo:[0,0,1] neg_hi:[0,0,1]
	v_pk_add_f32 v[12:13], v[86:87], v[98:99] neg_lo:[0,1] neg_hi:[0,1]
	v_and_b32_e32 v35, 0xffff0000, v14
	v_pk_add_f32 v[38:39], v[12:13], v[34:35]
	v_pk_add_f32 v[12:13], v[88:89], v[110:111] neg_lo:[0,1] neg_hi:[0,1]
	v_lshlrev_b32_e32 v14, 16, v15
	v_and_b32_e32 v15, 0xffff0000, v15
	v_pk_add_f32 v[58:59], v[12:13], v[14:15]
	v_min_i32_e32 v12, 7, v117
	v_add_u32_e32 v12, 1, v12
	v_cvt_f32_i32_e32 v69, v12
	v_pk_add_f32 v[22:23], v[22:23], v[28:29]
	v_pk_fma_f32 v[34:35], v[20:21], v[38:39], v[34:35] op_sel_hi:[0,1,1] neg_lo:[0,0,1] neg_hi:[0,0,1]
	v_pk_fma_f32 v[28:29], v[20:21], v[22:23], v[28:29] op_sel_hi:[0,1,1] neg_lo:[0,0,1] neg_hi:[0,0,1]
	v_cvt_pk_bf16_f32 v12, v28, v29
	v_div_scale_f32 v28, s[8:9], v69, v69, 1.0
	v_rcp_f32_e32 v29, v28
	v_pk_fma_f32 v[20:21], v[20:21], v[58:59], v[14:15] op_sel_hi:[0,1,1] neg_lo:[0,0,1] neg_hi:[0,0,1]
	v_cvt_pk_bf16_f32 v13, v32, v33
	v_cvt_pk_bf16_f32 v14, v34, v35
	v_cvt_pk_bf16_f32 v15, v20, v21
	global_store_dwordx4 v[26:27], v[12:15], off offset:1024
	v_lshlrev_b32_e32 v20, 16, v8
	v_and_b32_e32 v21, 0xffff0000, v8
	v_fma_f32 v12, -v28, v29, 1.0
	v_fmac_f32_e32 v29, v12, v29
	v_div_scale_f32 v12, vcc, 1.0, v69, 1.0
	v_mul_f32_e32 v13, v12, v29
	v_fma_f32 v14, -v28, v13, v12
	v_fmac_f32_e32 v13, v14, v29
	v_fma_f32 v12, -v28, v13, v12
	v_div_fmas_f32 v12, v12, v29, v13
	v_pk_add_f32 v[14:15], v[22:23], v[50:51] neg_lo:[0,1] neg_hi:[0,1]
	v_pk_add_f32 v[22:23], v[30:31], v[54:55] neg_lo:[0,1] neg_hi:[0,1]
	v_lshlrev_b32_e32 v8, 16, v9
	v_and_b32_e32 v9, 0xffff0000, v9
	v_div_fixup_f32 v12, v12, v69, 1.0
	v_pk_add_f32 v[22:23], v[22:23], v[8:9]
	v_lshlrev_b32_e32 v28, 16, v10
	v_pk_fma_f32 v[26:27], v[12:13], v[22:23], v[8:9] op_sel_hi:[0,1,1] neg_lo:[0,0,1] neg_hi:[0,0,1]
	v_pk_add_f32 v[8:9], v[38:39], v[90:91] neg_lo:[0,1] neg_hi:[0,1]
	v_and_b32_e32 v29, 0xffff0000, v10
	v_pk_add_f32 v[30:31], v[8:9], v[28:29]
	v_pk_add_f32 v[8:9], v[58:59], v[94:95] neg_lo:[0,1] neg_hi:[0,1]
	v_lshlrev_b32_e32 v10, 16, v11
	v_and_b32_e32 v11, 0xffff0000, v11
	v_pk_add_f32 v[32:33], v[8:9], v[10:11]
	v_min_i32_e32 v8, 7, v116
	v_add_u32_e32 v8, 1, v8
	v_cvt_f32_i32_e32 v34, v8
	v_pk_add_f32 v[14:15], v[14:15], v[20:21]
	v_pk_fma_f32 v[28:29], v[12:13], v[30:31], v[28:29] op_sel_hi:[0,1,1] neg_lo:[0,0,1] neg_hi:[0,0,1]
	v_pk_fma_f32 v[20:21], v[12:13], v[14:15], v[20:21] op_sel_hi:[0,1,1] neg_lo:[0,0,1] neg_hi:[0,0,1]
	v_cvt_pk_bf16_f32 v8, v20, v21
	v_div_scale_f32 v20, s[8:9], v34, v34, 1.0
	v_rcp_f32_e32 v21, v20
	v_pk_fma_f32 v[12:13], v[12:13], v[32:33], v[10:11] op_sel_hi:[0,1,1] neg_lo:[0,0,1] neg_hi:[0,0,1]
	v_cvt_pk_bf16_f32 v9, v26, v27
	v_cvt_pk_bf16_f32 v10, v28, v29
	v_cvt_pk_bf16_f32 v11, v12, v13
	global_store_dwordx4 v[18:19], v[8:11], off offset:1024
	v_lshlrev_b32_e32 v12, 16, v4
	v_and_b32_e32 v13, 0xffff0000, v4
	v_fma_f32 v8, -v20, v21, 1.0
	v_fmac_f32_e32 v21, v8, v21
	v_div_scale_f32 v8, vcc, 1.0, v34, 1.0
	v_mul_f32_e32 v9, v8, v21
	v_fma_f32 v10, -v20, v9, v8
	v_fmac_f32_e32 v9, v10, v21
	v_fma_f32 v8, -v20, v9, v8
	v_div_fmas_f32 v8, v8, v21, v9
	v_pk_add_f32 v[10:11], v[14:15], v[44:45] neg_lo:[0,1] neg_hi:[0,1]
	v_pk_add_f32 v[14:15], v[22:23], v[46:47] neg_lo:[0,1] neg_hi:[0,1]
	v_lshlrev_b32_e32 v4, 16, v5
	v_and_b32_e32 v5, 0xffff0000, v5
	v_div_fixup_f32 v8, v8, v34, 1.0
	v_pk_add_f32 v[14:15], v[14:15], v[4:5]
	v_lshlrev_b32_e32 v20, 16, v6
	v_pk_fma_f32 v[18:19], v[8:9], v[14:15], v[4:5] op_sel_hi:[0,1,1] neg_lo:[0,0,1] neg_hi:[0,0,1]
	v_pk_add_f32 v[4:5], v[30:31], v[52:53] neg_lo:[0,1] neg_hi:[0,1]
	v_and_b32_e32 v21, 0xffff0000, v6
	v_pk_add_f32 v[22:23], v[4:5], v[20:21]
	v_pk_add_f32 v[4:5], v[32:33], v[56:57] neg_lo:[0,1] neg_hi:[0,1]
	v_lshlrev_b32_e32 v6, 16, v7
	v_and_b32_e32 v7, 0xffff0000, v7
	v_pk_add_f32 v[26:27], v[4:5], v[6:7]
	v_min_i32_e32 v4, 7, v60
	v_add_u32_e32 v4, 1, v4
	v_cvt_f32_i32_e32 v28, v4
	v_pk_add_f32 v[10:11], v[10:11], v[12:13]
	v_pk_fma_f32 v[20:21], v[8:9], v[22:23], v[20:21] op_sel_hi:[0,1,1] neg_lo:[0,0,1] neg_hi:[0,0,1]
	v_pk_fma_f32 v[12:13], v[8:9], v[10:11], v[12:13] op_sel_hi:[0,1,1] neg_lo:[0,0,1] neg_hi:[0,0,1]
	v_cvt_pk_bf16_f32 v4, v12, v13
	v_div_scale_f32 v12, s[8:9], v28, v28, 1.0
	v_rcp_f32_e32 v13, v12
	v_pk_fma_f32 v[8:9], v[8:9], v[26:27], v[6:7] op_sel_hi:[0,1,1] neg_lo:[0,0,1] neg_hi:[0,0,1]
	v_cvt_pk_bf16_f32 v5, v18, v19
	v_cvt_pk_bf16_f32 v6, v20, v21
	v_cvt_pk_bf16_f32 v7, v8, v9
	global_store_dwordx4 v[24:25], v[4:7], off offset:1024
	v_lshlrev_b32_e32 v8, 16, v0
	v_and_b32_e32 v9, 0xffff0000, v0
	v_fma_f32 v4, -v12, v13, 1.0
	v_fmac_f32_e32 v13, v4, v13
	v_div_scale_f32 v4, vcc, 1.0, v28, 1.0
	v_mul_f32_e32 v5, v4, v13
	v_fma_f32 v6, -v12, v5, v4
	v_fmac_f32_e32 v5, v6, v13
	v_fma_f32 v4, -v12, v5, v4
	v_div_fmas_f32 v4, v4, v13, v5
	v_pk_add_f32 v[6:7], v[10:11], v[40:41] neg_lo:[0,1] neg_hi:[0,1]
	v_div_fixup_f32 v4, v4, v28, 1.0
	v_pk_add_f32 v[6:7], v[6:7], v[8:9]
	v_lshlrev_b32_e32 v0, 16, v1
	v_pk_fma_f32 v[6:7], v[4:5], v[6:7], v[8:9] op_sel_hi:[0,1,1] neg_lo:[0,0,1] neg_hi:[0,0,1]
	v_pk_add_f32 v[8:9], v[14:15], v[42:43] neg_lo:[0,1] neg_hi:[0,1]
	v_and_b32_e32 v1, 0xffff0000, v1
	v_pk_add_f32 v[8:9], v[8:9], v[0:1]
	v_lshlrev_b32_e32 v10, 16, v2
	v_pk_fma_f32 v[8:9], v[4:5], v[8:9], v[0:1] op_sel_hi:[0,1,1] neg_lo:[0,0,1] neg_hi:[0,0,1]
	v_pk_add_f32 v[0:1], v[22:23], v[36:37] neg_lo:[0,1] neg_hi:[0,1]
	v_and_b32_e32 v11, 0xffff0000, v2
	v_pk_add_f32 v[0:1], v[0:1], v[10:11]
	v_lshlrev_b32_e32 v2, 16, v3
	v_pk_fma_f32 v[10:11], v[4:5], v[0:1], v[10:11] op_sel_hi:[0,1,1] neg_lo:[0,0,1] neg_hi:[0,0,1]
	v_pk_add_f32 v[0:1], v[26:27], v[48:49] neg_lo:[0,1] neg_hi:[0,1]
	v_and_b32_e32 v3, 0xffff0000, v3
	v_pk_add_f32 v[0:1], v[0:1], v[2:3]
	s_nop 0
	v_pk_fma_f32 v[4:5], v[4:5], v[0:1], v[2:3] op_sel_hi:[0,1,1] neg_lo:[0,0,1] neg_hi:[0,0,1]
	v_cvt_pk_bf16_f32 v0, v6, v7
	v_cvt_pk_bf16_f32 v1, v8, v9
	v_cvt_pk_bf16_f32 v2, v10, v11
	v_cvt_pk_bf16_f32 v3, v4, v5
	global_store_dwordx4 v[16:17], v[0:3], off offset:1024
	s_cbranch_execnz .LBB0_386
	s_branch .LBB0_400
